# combine phase: the hoisted parameter vectors are now read directly by the consuming packed FMAs (24 register moves per row removed)
# baseline (speedup 1.0000x reference)
.LBB0_28:
	s_or_b64 exec, exec, s[8:9]
	v_lshlrev_b32_e32 v102, 16, v98
	v_and_b32_e32 v103, 0xffff0000, v98
	v_lshlrev_b32_e32 v98, 16, v99
	v_and_b32_e32 v99, 0xffff0000, v99
	v_pk_fma_f32 v[116:117], v[30:31], s[86:87], v[102:103] op_sel_hi:[1,0,1]
	v_lshlrev_b32_e32 v30, 16, v94
	v_and_b32_e32 v31, 0xffff0000, v94
	v_pk_fma_f32 v[114:115], v[32:33], s[86:87], v[98:99] op_sel_hi:[1,0,1]
	v_add_f32_e32 v0, v116, v117
	v_lshlrev_b32_e32 v32, 16, v95
	v_and_b32_e32 v33, 0xffff0000, v95
	v_pk_fma_f32 v[104:105], v[26:27], s[86:87], v[30:31] op_sel_hi:[1,0,1]
	v_add_f32_e32 v0, v114, v0
	v_pk_fma_f32 v[102:103], v[28:29], s[86:87], v[32:33] op_sel_hi:[1,0,1]
	v_add_f32_e32 v26, v104, v105
	v_add_f32_e32 v0, v115, v0
	v_add_f32_e32 v26, v102, v26
	v_add_f32_e32 v0, 0, v0
	v_and_b32_e32 v111, 0xffff0000, v96
	v_add_f32_e32 v26, v103, v26
	v_and_b32_e32 v99, 0xffff0000, v100
	v_lshlrev_b32_e32 v110, 16, v96
	v_mul_f32_e32 v89, v111, v111
	v_add_f32_e32 v0, v26, v0
	v_lshlrev_b32_e32 v98, 16, v100
	v_mul_f32_e32 v26, v99, v99
	v_lshlrev_b32_e32 v112, 16, v97
	v_fmac_f32_e32 v89, v110, v110
	v_lshlrev_b32_e32 v100, 16, v101
	v_fmac_f32_e32 v26, v98, v98
	v_and_b32_e32 v113, 0xffff0000, v97
	v_fmac_f32_e32 v89, v112, v112
	v_and_b32_e32 v101, 0xffff0000, v101
	v_fmac_f32_e32 v26, v100, v100
	v_fmac_f32_e32 v89, v113, v113
	v_fmac_f32_e32 v26, v101, v101
	v_add_f32_e32 v30, v89, v26
	v_lshlrev_b32_e32 v26, 16, v90
	v_and_b32_e32 v27, 0xffff0000, v90
	v_lshlrev_b32_e32 v28, 16, v91
	v_and_b32_e32 v29, 0xffff0000, v91
	v_pk_fma_f32 v[96:97], v[22:23], s[86:87], v[26:27] op_sel_hi:[1,0,1]
	v_pk_fma_f32 v[94:95], v[24:25], s[86:87], v[28:29] op_sel_hi:[1,0,1]
	v_add_f32_e32 v22, v96, v97
	v_add_f32_e32 v22, v94, v22
	v_add_f32_e32 v22, v95, v22
	v_and_b32_e32 v91, 0xffff0000, v92
	v_add_f32_e32 v0, v22, v0
	v_lshlrev_b32_e32 v90, 16, v92
	v_mul_f32_e32 v22, v91, v91
	v_lshlrev_b32_e32 v92, 16, v93
	v_fmac_f32_e32 v22, v90, v90
	v_and_b32_e32 v93, 0xffff0000, v93
	v_fmac_f32_e32 v22, v92, v92
	v_fmac_f32_e32 v22, v93, v93
	v_lshlrev_b32_e32 v24, 16, v84
	v_and_b32_e32 v25, 0xffff0000, v84
	v_add_f32_e32 v30, v22, v30
	v_lshlrev_b32_e32 v22, 16, v85
	v_and_b32_e32 v23, 0xffff0000, v85
	v_pk_fma_f32 v[24:25], v[18:19], s[86:87], v[24:25] op_sel_hi:[1,0,1]
	v_pk_fma_f32 v[22:23], v[20:21], s[86:87], v[22:23] op_sel_hi:[1,0,1]
	v_add_f32_e32 v18, v24, v25
	v_add_f32_e32 v18, v22, v18
	v_add_f32_e32 v18, v23, v18
	v_add_f32_e32 v0, v18, v0
	v_and_b32_e32 v27, 0xffff0000, v86
	v_lshlrev_b32_e32 v26, 16, v86
	v_mul_f32_e32 v18, v27, v27
	v_add_f32_dpp v0, v0, v0 quad_perm:[1,0,3,2] row_mask:0xf bank_mask:0xf bound_ctrl:1
	v_lshlrev_b32_e32 v28, 16, v87
	v_fmac_f32_e32 v18, v26, v26
	v_add_f32_dpp v0, v0, v0 quad_perm:[2,3,0,1] row_mask:0xf bank_mask:0xf bound_ctrl:1
	v_and_b32_e32 v29, 0xffff0000, v87
	v_fmac_f32_e32 v18, v28, v28
	v_add_f32_dpp v0, v0, v0 row_ror:4 row_mask:0xf bank_mask:0xf bound_ctrl:1
	v_fmac_f32_e32 v18, v29, v29
	v_add_f32_e32 v89, v18, v30
	v_add_f32_dpp v0, v0, v0 row_ror:8 row_mask:0xf bank_mask:0xf bound_ctrl:1
	ds_bpermute_b32 v18, v37, v0
	v_mov_b32_dpp v19, v89 quad_perm:[1,0,3,2] row_mask:0xf bank_mask:0xf bound_ctrl:1
	s_mov_b32 s2, 0x3a800000
	s_mov_b64 s[14:15], -1
	s_waitcnt lgkmcnt(0)
	v_add_f32_e32 v0, v0, v18
	ds_bpermute_b32 v18, v118, v0
	s_waitcnt lgkmcnt(0)
	v_add_f32_e32 v0, v0, v18
	v_fmamk_f32 v117, v0, 0xba800000, v117
	v_fmac_f32_e32 v116, 0xba800000, v0
	v_fmamk_f32 v85, v0, 0xba800000, v105
	v_fmac_f32_e32 v104, 0xba800000, v0
	v_mov_b32_e32 v84, v117
	v_fmac_f32_e32 v114, 0xba800000, v0
	v_fmac_f32_e32 v102, 0xba800000, v0
	v_mov_b32_e32 v20, v116
	v_mov_b32_e32 v21, v104
	v_pk_mul_f32 v[30:31], v[84:85], v[84:85]
	v_fmamk_f32 v33, v0, 0xba800000, v97
	v_fmac_f32_e32 v96, 0xba800000, v0
	v_fmamk_f32 v32, v0, 0xba800000, v25
	v_fmamk_f32 v115, v0, 0xba800000, v115
	v_pk_fma_f32 v[20:21], v[20:21], v[20:21], v[30:31]
	v_mov_b32_e32 v30, v114
	v_mov_b32_e32 v31, v102
	v_fmac_f32_e32 v94, 0xba800000, v0
	v_fmac_f32_e32 v24, 0xba800000, v0
	v_mov_b32_e32 v25, v96
	v_pk_mul_f32 v[86:87], v[32:33], v[32:33]
	v_fmamk_f32 v109, v0, 0xba800000, v103
	v_pk_fma_f32 v[20:21], v[30:31], v[30:31], v[20:21]
	v_mov_b32_e32 v108, v115
	v_fmamk_f32 v30, v0, 0xba800000, v23
	v_fmac_f32_e32 v22, 0xba800000, v0
	v_pk_fma_f32 v[86:87], v[24:25], v[24:25], v[86:87]
	v_mov_b32_e32 v23, v94
	v_pk_fma_f32 v[20:21], v[108:109], v[108:109], v[20:21]
	v_fmamk_f32 v31, v0, 0xba800000, v95
	v_pk_fma_f32 v[86:87], v[22:23], v[22:23], v[86:87]
	v_pk_add_f32 v[20:21], v[20:21], v[20:21] op_sel:[0,1] op_sel_hi:[1,0]
	v_pk_fma_f32 v[86:87], v[30:31], v[30:31], v[86:87]
	s_nop 0
	v_pk_add_f32 v[20:21], v[86:87], v[20:21] op_sel:[1,0] op_sel_hi:[0,1]
	v_pk_add_f32 v[20:21], v[86:87], v[20:21]
	s_nop 0
	v_mov_b32_e32 v21, v89
	v_mov_b32_dpp v18, v20 quad_perm:[1,0,3,2] row_mask:0xf bank_mask:0xf bound_ctrl:1
	v_pk_add_f32 v[18:19], v[20:21], v[18:19]
	s_nop 1
	v_mov_b32_dpp v21, v19 quad_perm:[2,3,0,1] row_mask:0xf bank_mask:0xf bound_ctrl:1
	v_mov_b32_dpp v20, v18 quad_perm:[2,3,0,1] row_mask:0xf bank_mask:0xf bound_ctrl:1
	v_pk_add_f32 v[18:19], v[18:19], v[20:21]
	s_nop 1
	v_mov_b32_dpp v21, v19 row_ror:4 row_mask:0xf bank_mask:0xf bound_ctrl:1
	v_mov_b32_dpp v20, v18 row_ror:4 row_mask:0xf bank_mask:0xf bound_ctrl:1
	v_pk_add_f32 v[18:19], v[18:19], v[20:21]
	s_nop 1
	v_mov_b32_dpp v21, v19 row_ror:8 row_mask:0xf bank_mask:0xf bound_ctrl:1
	v_mov_b32_dpp v20, v18 row_ror:8 row_mask:0xf bank_mask:0xf bound_ctrl:1
	v_pk_add_f32 v[18:19], v[18:19], v[20:21]
	ds_bpermute_b32 v21, v37, v19
	ds_bpermute_b32 v20, v37, v18
	s_waitcnt lgkmcnt(0)
	v_pk_add_f32 v[18:19], v[18:19], v[20:21]
	ds_bpermute_b32 v21, v118, v19
	ds_bpermute_b32 v20, v118, v18
	s_waitcnt lgkmcnt(0)
	v_pk_add_f32 v[18:19], v[18:19], v[20:21]
	s_nop 0
	v_pk_fma_f32 v[18:19], v[18:19], s[2:3], v[138:139] op_sel_hi:[1,0,1]
	s_movk_i32 s2, 0xfff
	v_mul_f32_e32 v0, 0x4b800000, v19
	v_cmp_gt_f32_e64 s[8:9], s33, v19
	v_cmp_gt_f32_e32 vcc, s33, v18
	s_nop 0
	v_cndmask_b32_e64 v0, v19, v0, s[8:9]
	v_rsq_f32_e32 v0, v0
	s_nop 0
	v_mul_f32_e32 v19, 0x45800000, v0
	v_cndmask_b32_e64 v84, v0, v19, s[8:9]
	v_mul_f32_e32 v0, 0x4b800000, v18
	v_cndmask_b32_e32 v0, v18, v0, vcc
	v_rsq_f32_e32 v0, v0
	s_nop 0
	v_mul_f32_e32 v18, 0x45800000, v0
	v_cndmask_b32_e32 v86, v0, v18, vcc
	v_pk_mul_f32 v[18:19], v[114:115], v[86:87] op_sel_hi:[1,0]
	v_pk_mul_f32 v[20:21], v[116:117], v[86:87] op_sel_hi:[1,0]
	v_and_b32_e32 v0, 0xfff, v88
	v_cmp_ne_u32_e64 s[10:11], s2, v0
	v_cmp_eq_u32_e64 s[8:9], 0, v0
	v_cndmask_b32_e64 v0, 0, 1, s[24:25]
	s_and_b64 vcc, exec, s[22:23]
	v_cmp_ne_u32_e64 s[12:13], 1, v0
	v_pk_fma_f32 v[114:115], v[176:177], v[20:21], v[192:193]
	v_pk_fma_f32 v[116:117], v[178:179], v[18:19], v[194:195]
	v_lshlrev_b32_e32 v18, 16, v106
	v_and_b32_e32 v19, 0xffff0000, v106
	v_lshlrev_b32_e32 v20, 16, v107
	v_and_b32_e32 v21, 0xffff0000, v107
	v_pk_mul_f32 v[20:21], v[112:113], v[20:21]
	v_pk_mul_f32 v[18:19], v[110:111], v[18:19]
	v_pk_mul_f32 v[110:111], v[20:21], v[84:85] op_sel_hi:[1, 0]
	v_pk_mul_f32 v[106:107], v[18:19], v[84:85] op_sel_hi:[1, 0]
	v_pk_fma_f32 v[112:113], v[216:217], v[110:111], v[116:117]
	v_pk_fma_f32 v[110:111], v[214:215], v[106:107], v[114:115]
	v_lshl_add_u64 v[18:19], v[54:55], 0, s[28:29]
	v_cvt_pk_bf16_f32 v106, v110, v111
	v_cvt_pk_bf16_f32 v107, v112, v113
	global_store_dwordx4 v[18:19], v[110:113], off nt
	s_cbranch_vccz .LBB0_32
	s_and_b64 vcc, exec, s[12:13]
	s_cbranch_vccnz .LBB0_31
	v_lshl_add_u64 v[20:21], v[52:53], 0, v[46:47]
	global_store_dwordx2 v[20:21], v[106:107], off

.LBB0_37:
	v_mov_b32_e32 v105, v85
	v_mov_b32_e32 v87, v86
	v_mov_b32_e32 v106, v86
	v_mov_b32_e32 v107, v86
	v_mov_b32_e32 v103, v109
	v_pk_mul_f32 v[110:111], v[102:103], v[106:107]
	v_pk_mul_f32 v[112:113], v[104:105], v[86:87]
	v_mov_b32_e32 v85, v84
	v_cndmask_b32_e64 v0, 0, 1, s[22:23]
	s_mov_b64 s[30:31], -1
	v_cmp_ne_u32_e64 s[14:15], 1, v0
	s_andn2_b64 vcc, exec, s[22:23]
	v_pk_fma_f32 v[102:103], v[112:113], v[180:181], v[196:197]
	v_lshlrev_b32_e32 v106, 16, v82
	v_and_b32_e32 v107, 0xffff0000, v82
	v_lshlrev_b32_e32 v82, 16, v83
	v_and_b32_e32 v83, 0xffff0000, v83
	v_pk_mul_f32 v[98:99], v[98:99], v[106:107]
	v_pk_mul_f32 v[82:83], v[100:101], v[82:83]
	v_pk_mul_f32 v[106:107], v[98:99], v[84:85]
	v_mov_b32_e32 v98, v84
	v_mov_b32_e32 v99, v84
	v_pk_mul_f32 v[82:83], v[82:83], v[98:99]
	v_pk_fma_f32 v[104:105], v[110:111], v[182:183], v[198:199]
	v_pk_fma_f32 v[98:99], v[106:107], v[218:219], v[102:103]
	v_pk_fma_f32 v[100:101], v[82:83], v[220:221], v[104:105]
	v_cvt_pk_bf16_f32 v82, v98, v99
	v_cvt_pk_bf16_f32 v83, v100, v101
	global_store_dwordx4 v[18:19], v[98:101], off offset:1024 nt
	s_cbranch_vccnz .LBB0_41
	s_and_b64 vcc, exec, s[12:13]
	s_cbranch_vccnz .LBB0_40
	v_lshl_add_u64 v[98:99], v[52:53], 0, v[46:47]
	global_store_dwordx2 v[98:99], v[82:83], off offset:512

.LBB0_46:
	v_mov_b32_e32 v97, v33
	v_mov_b32_e32 v82, v86
	v_mov_b32_e32 v83, v86
	v_mov_b32_e32 v95, v31
	v_pk_mul_f32 v[82:83], v[94:95], v[82:83]
	v_pk_mul_f32 v[102:103], v[96:97], v[86:87]
	s_mov_b64 s[30:31], -1
	s_and_b64 vcc, exec, s[14:15]
	v_pk_fma_f32 v[96:97], v[82:83], v[186:187], v[208:209]
	v_lshlrev_b32_e32 v82, 16, v80
	v_and_b32_e32 v83, 0xffff0000, v80
	v_lshlrev_b32_e32 v80, 16, v81
	v_and_b32_e32 v81, 0xffff0000, v81
	v_pk_mul_f32 v[82:83], v[90:91], v[82:83]
	v_pk_mul_f32 v[80:81], v[92:93], v[80:81]
	v_pk_mul_f32 v[90:91], v[82:83], v[84:85]
	v_mov_b32_e32 v82, v84
	v_mov_b32_e32 v83, v84
	v_pk_mul_f32 v[92:93], v[80:81], v[82:83]
	v_pk_fma_f32 v[94:95], v[102:103], v[184:185], v[206:207]
	v_pk_fma_f32 v[82:83], v[92:93], v[224:225], v[96:97]
	v_pk_fma_f32 v[80:81], v[90:91], v[222:223], v[94:95]
	global_store_dwordx4 v[18:19], v[80:83], off offset:2048 nt
	s_nop 1
	v_cvt_pk_bf16_f32 v80, v80, v81
	v_cvt_pk_bf16_f32 v81, v82, v83
	s_cbranch_vccnz .LBB0_50
	s_and_b64 vcc, exec, s[12:13]
	s_cbranch_vccnz .LBB0_49
	v_lshl_add_u64 v[82:83], v[52:53], 0, v[46:47]
	global_store_dwordx2 v[82:83], v[80:81], off offset:1024

.LBB0_55:
	v_mov_b32_e32 v23, v30
	v_lshlrev_b32_e32 v30, 16, v34
	v_and_b32_e32 v31, 0xffff0000, v34
	v_mov_b32_e32 v25, v32
	v_mov_b32_e32 v32, v86
	v_mov_b32_e32 v33, v86
	v_lshlrev_b32_e32 v34, 16, v35
	v_and_b32_e32 v35, 0xffff0000, v35
	v_pk_mul_f32 v[26:27], v[26:27], v[30:31]
	v_pk_mul_f32 v[22:23], v[22:23], v[32:33]
	v_pk_mul_f32 v[24:25], v[24:25], v[86:87]
	v_pk_mul_f32 v[28:29], v[28:29], v[34:35]
	v_pk_mul_f32 v[26:27], v[26:27], v[84:85]
	v_mov_b32_e32 v85, v84
	v_pk_mul_f32 v[28:29], v[28:29], v[84:85]
	s_and_b64 vcc, exec, s[14:15]
	s_mov_b64 s[14:15], -1
	s_waitcnt vmcnt(1)
	v_pk_fma_f32 v[22:23], v[22:23], v[190:191], v[212:213]
	v_pk_fma_f32 v[30:31], v[24:25], v[188:189], v[210:211]
	s_waitcnt vmcnt(0)
	v_pk_fma_f32 v[24:25], v[28:29], v[228:229], v[22:23]
	v_pk_fma_f32 v[22:23], v[26:27], v[226:227], v[30:31]
	global_store_dwordx4 v[18:19], v[22:25], off offset:3072 nt
	v_cvt_pk_bf16_f32 v18, v22, v23
	v_cvt_pk_bf16_f32 v19, v24, v25
	s_cbranch_vccnz .LBB0_59
	s_and_b64 vcc, exec, s[12:13]
	s_cbranch_vccnz .LBB0_58
	v_lshl_add_u64 v[22:23], v[52:53], 0, v[46:47]
	global_store_dwordx2 v[22:23], v[18:19], off offset:1536
